# LN: residual-stream row loads without the nt hint (stores keep it)
# speedup vs baseline: 1.0720x; 1.0062x over previous
; DI int opqv(int x) { asm volatile("" : "+v"(x)); return x; }
; DI char* opq(char* p) { asm volatile("" : "+s"(p)); return p; }
; DI void ln_phase(const Params& p, int ls) {
;   const int tid = opqv(threadIdx.x), lane = tid & 63, w = tid >> 6;
;   char* ws = opq(p.ws);
;   const float* mod = (const float*)(ws + OFF_MOD);
;   u16* hy = (u16*)(ws + OFF_HY);
;   const float* xin = (ls == 0) ? p.x : p.out;
;   const float* lg = p.ln_g + ls * 1024; const float* lb = p.ln_b + ls * 1024;
;   const int stride = gridDim.x * 8;
;   f32x4 xc[4], xn[4]; uint2 yc[4], yn[4];
;   {
;     const int row = blockIdx.x * 8 + w;
; #pragma unroll
;     for (int i = 0; i < 4; ++i) {
;       const int col = lane * 4 + 256 * i;
;       xc[i] = __builtin_nontemporal_load((const f32x4*)(xin + (size_t)row * 1024 + col));
;       yc[i] = *(const uint2*)(hy + (size_t)row * LDH + col);
;     }
;   }
;   for (int row = blockIdx.x * 8 + w; row < T_; row += stride) {
;     const int b = row >> 14;
;     const float* gate = mod + (ls * 2 + b) * 3072 + 2048;
;     const int rn = row + stride;
;     if (rn < T_) {
; #pragma unroll
;       for (int i = 0; i < 4; ++i) {
;         const int col = lane * 4 + 256 * i;
;         xn[i] = __builtin_nontemporal_load((const f32x4*)(xin + (size_t)rn * 1024 + col));
;         yn[i] = *(const uint2*)(hy + (size_t)rn * LDH + col);
;       }
;     }
.LBB0_847:
	s_andn2_b64 vcc, exec, s[4:5]
	v_readlane_b32 s27, v254, 34
	s_cbranch_vccnz .LBB0_862
	s_waitcnt lgkmcnt(0)
	v_mov_b32_e32 v1, v182
	v_readlane_b32 s0, v253, 52
	v_ashrrev_i32_e32 v0, 6, v1
	v_readlane_b32 s6, v251, 13
	v_add_u32_e32 v62, s0, v0
	s_mov_b32 s0, 0x8000
	v_readlane_b32 s7, v251, 14
	v_cmp_gt_i32_e32 vcc, s0, v62
	s_and_saveexec_b64 s[8:9], vcc
	s_cbranch_execz .LBB0_861
	v_readlane_b32 s22, v254, 33
	v_readlane_b32 s24, v251, 1
	s_mov_b64 s[10:11], s[62:63]
	v_readlane_b32 s52, v251, 19
	v_readlane_b32 s0, v253, 58
	s_cmp_eq_u32 s22, 0
	v_readlane_b32 s30, v251, 7
	v_readlane_b32 s31, v251, 8
	v_readlane_b32 s53, v251, 20
	v_readlane_b32 s1, v253, 59
	s_mov_b32 s20, s0
	s_cselect_b32 s1, s53, s31
	s_cselect_b32 s0, s52, s30
	s_mov_b64 s[4:5], 0x8c04100
	s_mov_b32 s4, 0x8c04000
	s_lshl_b32 s4, s22, 10
	s_ashr_i32 s5, s4, 31
	v_readlane_b32 s62, v251, 29
	s_lshl_b64 s[4:5], s[4:5], 2
	v_readlane_b32 s63, v251, 30
	s_add_u32 s12, s62, s4
	v_readlane_b32 s60, v251, 27
	s_addc_u32 s13, s63, s5
	v_readlane_b32 s61, v251, 28
	s_add_u32 s4, s60, s4
	s_addc_u32 s5, s61, s5
	v_readlane_b32 s4, v253, 53
	v_readlane_b32 s25, v251, 2
	v_readlane_b32 s28, v251, 5
	v_readlane_b32 s29, v251, 6
	s_lshl_b32 s14, s22, 1
	v_readlane_b32 s26, v251, 3
	v_readlane_b32 s27, v251, 4
	v_readlane_b32 s64, v251, 31
	v_readlane_b32 s65, v251, 32
	v_readlane_b32 s66, v251, 33
	v_readlane_b32 s67, v251, 34
	v_readlane_b32 s28, v253, 60
	v_readlane_b32 s24, v253, 41
	s_cmp_lt_i32 s22, 7
	v_readlane_b32 s27, v254, 34
	s_mov_b32 s34, 0x3fd744fd
	s_mov_b64 s[64:65], 0x80
	v_readlane_b32 s29, v253, 61
	s_movk_i32 s67, 0x1ff
	s_movk_i32 s66, 0x60
	s_mov_b32 s26, 0x8000
	s_mov_b32 s15, 0x800000
	v_readlane_b32 s25, v253, 42
	s_mov_b64 s[62:63], s[10:11]
	s_cselect_b64 s[10:11], -1, 0
	s_mov_b64 s[12:13], 0
	v_readlane_b32 s54, v251, 21
	v_readlane_b32 s55, v251, 22
	v_readlane_b32 s56, v251, 23
	v_readlane_b32 s57, v251, 24
	v_readlane_b32 s58, v251, 25
	v_readlane_b32 s59, v251, 26
	s_nop 4
	s_mov_b64 s[12:13], s[0:1]
	v_and_b32_e32 v1, 63, v182
	v_lshlrev_b32_e32 v160, 4, v1
	v_lshlrev_b32_e32 v236, 3, v1
	v_readfirstlane_b32 s100, v62
	s_mov_b32 s101, 0
	s_nop 0
	s_lshl_b32 s0, s100, 12
	s_add_u32 s0, s12, s0
	s_addc_u32 s1, s13, 0
	global_load_dwordx4 v[0:3], v160, s[0:1]
	global_load_dwordx4 v[4:7], v160, s[0:1] offset:1024
	global_load_dwordx4 v[8:11], v160, s[0:1] offset:2048
	global_load_dwordx4 v[12:15], v160, s[0:1] offset:3072
	s_mul_i32 s0, s100, 0x880
	s_add_u32 s0, s6, s0
	s_addc_u32 s1, s7, 0
	s_add_u32 s0, s0, 0x8c04100
	s_addc_u32 s1, s1, 0
	global_load_dwordx2 v[48:49], v236, s[0:1]
	global_load_dwordx2 v[50:51], v236, s[0:1] offset:512
	global_load_dwordx2 v[52:53], v236, s[0:1] offset:1024
	global_load_dwordx2 v[54:55], v236, s[0:1] offset:1536
	s_mov_b32 s4, s100
	s_add_i32 s4, s4, s20
	s_cmp_lt_u32 s4, 0x8000
	s_cbranch_scc0 .Lln_no1
	s_lshl_b32 s0, s4, 12
	s_add_u32 s0, s12, s0
	s_addc_u32 s1, s13, 0
	global_load_dwordx4 v[16:19], v160, s[0:1]
	global_load_dwordx4 v[20:23], v160, s[0:1] offset:1024
	global_load_dwordx4 v[24:27], v160, s[0:1] offset:2048
	global_load_dwordx4 v[28:31], v160, s[0:1] offset:3072
	s_mul_i32 s0, s4, 0x880
	s_add_u32 s0, s6, s0
	s_addc_u32 s1, s7, 0
	s_add_u32 s0, s0, 0x8c04100
	s_addc_u32 s1, s1, 0
	global_load_dwordx2 v[56:57], v236, s[0:1]
	global_load_dwordx2 v[58:59], v236, s[0:1] offset:512
	global_load_dwordx2 v[60:61], v236, s[0:1] offset:1024
	global_load_dwordx2 v[62:63], v236, s[0:1] offset:1536

; DI void ln_phase(const Params& p, int ls) {
;     ...
;     const int rn = row + stride;
;     if (rn < T_) {
; #pragma unroll
;       for (int i = 0; i < 4; ++i) {
;         const int col = lane * 4 + 256 * i;
;         xn[i] = __builtin_nontemporal_load((const f32x4*)(xin + (size_t)rn * 1024 + col));
;         yn[i] = *(const uint2*)(hy + (size_t)rn * LDH + col);
;       }
;     }
.Lln_pskip2_init:
.Lln_it0:
	s_mul_i32 s4, s20, 2
	s_add_i32 s4, s100, s4
	s_cmp_lt_u32 s4, 0x8000
	s_cbranch_scc0 .Lln_nopf0
	s_lshl_b32 s0, s4, 12
	s_add_u32 s0, s12, s0
	s_addc_u32 s1, s13, 0
	global_load_dwordx4 v[32:35], v160, s[0:1]
	global_load_dwordx4 v[36:39], v160, s[0:1] offset:1024
	global_load_dwordx4 v[40:43], v160, s[0:1] offset:2048
	global_load_dwordx4 v[44:47], v160, s[0:1] offset:3072
	s_mul_i32 s0, s4, 0x880
	s_add_u32 s0, s6, s0
	s_addc_u32 s1, s7, 0
	s_add_u32 s0, s0, 0x8c04100
	s_addc_u32 s1, s1, 0
	global_load_dwordx2 v[64:65], v236, s[0:1]
	global_load_dwordx2 v[66:67], v236, s[0:1] offset:512
	global_load_dwordx2 v[68:69], v236, s[0:1] offset:1024
	global_load_dwordx2 v[70:71], v236, s[0:1] offset:1536

; DI void ln_phase(const Params& p, int ls) {
;     ...
;     const int rn = row + stride;
;     if (rn < T_) {
; #pragma unroll
;       for (int i = 0; i < 4; ++i) {
;         const int col = lane * 4 + 256 * i;
;         xn[i] = __builtin_nontemporal_load((const f32x4*)(xin + (size_t)rn * 1024 + col));
;         yn[i] = *(const uint2*)(hy + (size_t)rn * LDH + col);
;       }
;     }
.Lln_it1:
	s_mul_i32 s4, s20, 2
	s_add_i32 s4, s100, s4
	s_cmp_lt_u32 s4, 0x8000
	s_cbranch_scc0 .Lln_nopf1
	s_lshl_b32 s0, s4, 12
	s_add_u32 s0, s12, s0
	s_addc_u32 s1, s13, 0
	global_load_dwordx4 v[0:3], v160, s[0:1]
	global_load_dwordx4 v[4:7], v160, s[0:1] offset:1024
	global_load_dwordx4 v[8:11], v160, s[0:1] offset:2048
	global_load_dwordx4 v[12:15], v160, s[0:1] offset:3072
	s_mul_i32 s0, s4, 0x880
	s_add_u32 s0, s6, s0
	s_addc_u32 s1, s7, 0
	s_add_u32 s0, s0, 0x8c04100
	s_addc_u32 s1, s1, 0
	global_load_dwordx2 v[48:49], v236, s[0:1]
	global_load_dwordx2 v[50:51], v236, s[0:1] offset:512
	global_load_dwordx2 v[52:53], v236, s[0:1] offset:1024
	global_load_dwordx2 v[54:55], v236, s[0:1] offset:1536

; DI void ln_phase(const Params& p, int ls) {
;     ...
;     const int rn = row + stride;
;     if (rn < T_) {
; #pragma unroll
;       for (int i = 0; i < 4; ++i) {
;         const int col = lane * 4 + 256 * i;
;         xn[i] = __builtin_nontemporal_load((const f32x4*)(xin + (size_t)rn * 1024 + col));
;         yn[i] = *(const uint2*)(hy + (size_t)rn * LDH + col);
;       }
;     }
.Lln_it2:
	s_mul_i32 s4, s20, 2
	s_add_i32 s4, s100, s4
	s_cmp_lt_u32 s4, 0x8000
	s_cbranch_scc0 .Lln_nopf2
	s_lshl_b32 s0, s4, 12
	s_add_u32 s0, s12, s0
	s_addc_u32 s1, s13, 0
	global_load_dwordx4 v[16:19], v160, s[0:1]
	global_load_dwordx4 v[20:23], v160, s[0:1] offset:1024
	global_load_dwordx4 v[24:27], v160, s[0:1] offset:2048
	global_load_dwordx4 v[28:31], v160, s[0:1] offset:3072
	s_mul_i32 s0, s4, 0x880
	s_add_u32 s0, s6, s0
	s_addc_u32 s1, s7, 0
	s_add_u32 s0, s0, 0x8c04100
	s_addc_u32 s1, s1, 0
	global_load_dwordx2 v[56:57], v236, s[0:1]
	global_load_dwordx2 v[58:59], v236, s[0:1] offset:512
	global_load_dwordx2 v[60:61], v236, s[0:1] offset:1024
	global_load_dwordx2 v[62:63], v236, s[0:1] offset:1536
